# code placement: everything from the differential-mixer tile loop onward shifted by 4 bytes (one s_nop before the loop head)
# baseline (speedup 1.0000x reference)
.LBB0_734:
	s_lshl_b32 s1, s11, 5
	s_and_b32 s0, s11, 0xffffff00
	s_and_b32 s1, s1, 0xe0
	s_or_b32 s0, s1, s0
	s_bfe_u32 s1, s11, 0x50003
	s_or_b32 s6, s0, s1
	v_readlane_b32 s0, v254, 15
	v_readlane_b32 s1, v254, 16
	s_and_b64 s[0:1], s[0:1], exec
	v_mov_b32_e32 v0, v185
	s_cselect_b32 s14, s6, s11
	s_lshl_b32 s6, s14, 3
	v_mbcnt_lo_u32_b32 v0, -1, v0
	v_mbcnt_hi_u32_b32 v12, -1, v0
	v_readlane_b32 s0, v252, 16
	s_and_b32 s12, s6, 0xc0
	s_ashr_i32 s15, s14, 5
	v_add_u32_e32 v2, s0, v12
	s_mov_b64 s[0:1], s[40:41]
	s_lshl_b32 s6, s12, 1
	s_add_u32 s6, s0, s6
	s_addc_u32 s7, s1, 0
	s_add_u32 s16, s6, 0xba00a00
	s_addc_u32 s17, s7, 0
	s_add_u32 s8, s6, 0xba00c00
	s_addc_u32 s9, s7, 0
	s_add_u32 s6, s6, 0xba00e00
	s_addc_u32 s7, s7, 0
	s_lshl_b32 s14, s14, 8
	v_and_b32_e32 v13, 31, v12
	s_lshl_b32 s13, s15, 11
	s_and_b32 s18, s14, 0x700
	s_lshl_b32 s14, s15, 8
	v_readlane_b32 s15, v255, 6
	v_bfe_u32 v14, v12, 5, 1
	v_lshlrev_b32_e32 v184, 4, v14
	v_or_b32_e32 v0, s15, v13
	s_or_b32 s15, s18, s13
	v_add_u32_e32 v192, s15, v0
	v_mov_b64_e32 v[0:1], s[16:17]
	v_mad_i64_i32 v[0:1], s[16:17], v192, s33, v[0:1]
	v_lshl_add_u64 v[0:1], v[0:1], 0, v[184:185]
	global_load_dwordx4 v[128:131], v[0:1], off
	global_load_dwordx4 v[132:135], v[0:1], off offset:32
	global_load_dwordx4 v[136:139], v[0:1], off offset:64
	global_load_dwordx4 v[140:143], v[0:1], off offset:96
	v_ashrrev_i32_e32 v0, 31, v2
	v_lshrrev_b32_e32 v0, 29, v0
	v_add_u32_e32 v0, v2, v0
	v_ashrrev_i32_e32 v239, 3, v0
	v_and_b32_e32 v0, -8, v0
	v_sub_u32_e32 v15, v2, v0
	v_ashrrev_i32_e32 v240, 3, v2
	v_add_u32_e32 v2, s13, v239
	v_mov_b64_e32 v[0:1], s[8:9]
	v_mad_i64_i32 v[0:1], s[16:17], v2, s33, v[0:1]
	v_lshlrev_b32_e32 v2, 3, v15
	v_ashrrev_i32_e32 v3, 31, v2
	v_lshlrev_b64 v[8:9], 1, v[2:3]
	v_lshl_add_u64 v[0:1], v[0:1], 0, v[8:9]
	global_load_dwordx4 v[0:3], v[0:1], off
	v_and_b32_e32 v6, 7, v12
	v_add_u32_e32 v7, s13, v240
	v_mov_b64_e32 v[4:5], s[6:7]
	v_mad_i64_i32 v[4:5], s[16:17], v7, s33, v[4:5]
	v_lshlrev_b32_e32 v10, 4, v6
	v_mov_b32_e32 v11, v185
	v_lshl_add_u64 v[4:5], v[4:5], 0, v[10:11]
	global_load_dwordx4 v[4:7], v[4:5], off
	v_mul_lo_u32 v16, v239, s81
	v_lshlrev_b32_e32 v15, 4, v15
	v_add3_u32 v241, 0, v16, v15
	v_lshlrev_b32_e32 v191, 2, v14
	v_lshl_add_u64 v[196:197], s[6:7], 0, v[10:11]
	s_or_b32 s7, s13, 64
	v_lshl_add_u64 v[194:195], s[8:9], 0, v[8:9]
	s_add_i32 s14, s14, 0x8000
	v_ashrrev_i32_e32 v193, 31, v192
	v_lshlrev_b32_e32 v190, 3, v14
	s_mov_b32 s6, 2
	s_waitcnt vmcnt(1)
	ds_write_b128 v241, v[0:3]
	v_mul_lo_u32 v0, v240, s80
	v_add3_u32 v242, 0, v0, v10
	v_lshrrev_b32_e32 v0, 2, v12
	v_lshlrev_b32_e32 v1, 2, v12
	v_and_b32_e32 v3, 16, v12
	v_and_or_b32 v0, v0, 3, v191
	v_and_or_b32 v1, v1, 12, v3
	v_mul_u32_u24_e32 v0, 0xc0, v0
	v_lshlrev_b32_e32 v1, 1, v1
	s_waitcnt vmcnt(0)
	ds_write_b128 v242, v[4:7] offset:26624
	v_add3_u32 v243, 0, v0, v1
	v_add_u32_e32 v0, s7, v239
	s_waitcnt lgkmcnt(0)
	s_barrier
	v_mad_i64_i32 v[0:1], s[8:9], v0, s33, v[194:195]
	global_load_dwordx4 v[82:85], v[0:1], off
	v_add_u32_e32 v0, s7, v240
	v_mad_i64_i32 v[0:1], s[8:9], v0, s33, v[196:197]
	global_load_dwordx4 v[86:89], v[0:1], off
	v_mul_u32_u24_e32 v2, 0xd0, v13
	v_add3_u32 v184, 0, v2, v184
	ds_read_b128 v[16:19], v184 offset:6656
	ds_read_b128 v[0:3], v184
	ds_read_b128 v[32:35], v184 offset:32
	ds_read_b128 v[36:39], v184 offset:6688
	ds_read_b64_tr_b16 v[66:67], v243 offset:26624
	ds_read_b64_tr_b16 v[68:69], v243 offset:28160
	ds_read_b64_tr_b16 v[98:99], v243 offset:29696
	ds_read_b64_tr_b16 v[100:101], v243 offset:31232
	ds_read_b64_tr_b16 v[94:95], v243 offset:32768
	ds_read_b64_tr_b16 v[96:97], v243 offset:34304
	ds_read_b64_tr_b16 v[90:91], v243 offset:35840
	ds_read_b64_tr_b16 v[92:93], v243 offset:37376
	ds_read_b64_tr_b16 v[102:103], v243 offset:26688
	ds_read_b64_tr_b16 v[104:105], v243 offset:28224
	ds_read_b64_tr_b16 v[114:115], v243 offset:29760
	ds_read_b64_tr_b16 v[116:117], v243 offset:31296
	ds_read_b64_tr_b16 v[110:111], v243 offset:32832
	ds_read_b64_tr_b16 v[112:113], v243 offset:34368
	ds_read_b64_tr_b16 v[106:107], v243 offset:35904
	ds_read_b64_tr_b16 v[108:109], v243 offset:37440
	s_waitcnt lgkmcnt(14)
	v_mfma_f32_32x32x16_bf16 v[0:15], v[0:3], v[128:131], 0
	v_mfma_f32_32x32x16_bf16 v[16:31], v[16:19], v[128:131], 0
	v_mfma_f32_32x32x16_bf16 v[0:15], v[32:35], v[132:135], v[0:15]
	v_mfma_f32_32x32x16_bf16 v[16:31], v[36:39], v[132:135], v[16:31]
	s_nop 15
	s_nop 7
	s_nop 0
	v_max3_f32 v32, v0, v1, v16
	v_max3_f32 v33, v2, v3, v17
	s_nop 0
	v_max3_f32 v32, v32, v18, v19
	v_max3_f32 v33, v33, v6, v7
	s_nop 0
	v_max3_f32 v32, v32, v4, v5
	v_max3_f32 v33, v33, v22, v23
	s_nop 0
	v_max3_f32 v32, v32, v20, v21
	v_max3_f32 v33, v33, v10, v11
	s_nop 0
	v_max3_f32 v32, v32, v8, v9
	v_max3_f32 v33, v33, v26, v27
	s_nop 0
	v_max3_f32 v32, v32, v24, v25
	v_max3_f32 v33, v33, v14, v15
	s_nop 0
	v_max3_f32 v32, v32, v12, v13
	v_max3_f32 v33, v33, v30, v31
	s_nop 0
	v_max3_f32 v32, v32, v28, v29
	s_nop 0
	v_max_f32_e32 v32, v32, v33
	s_nop 0
	v_mov_b32_e32 v33, v32
	s_nop 1
	v_permlane32_swap_b32_e32 v32, v33
	v_max_f32_e32 v33, v33, v33
	v_max_f32_e32 v32, v32, v32
	v_max_f32_e32 v32, v32, v33
	v_sub_f32_e32 v0, v0, v32
	v_sub_f32_e32 v1, v1, v32
	v_sub_f32_e32 v16, v16, v32
	v_sub_f32_e32 v17, v17, v32
	v_exp_f32_e32 v0, v0
	v_exp_f32_e32 v1, v1
	v_sub_f32_e32 v2, v2, v32
	v_sub_f32_e32 v3, v3, v32
	v_sub_f32_e32 v33, v4, v32
	v_sub_f32_e32 v34, v5, v32
	v_exp_f32_e32 v4, v16
	v_exp_f32_e32 v5, v17
	v_sub_f32_e32 v18, v18, v32
	v_sub_f32_e32 v19, v19, v32
	v_exp_f32_e32 v2, v2
	v_exp_f32_e32 v3, v3
	v_sub_f32_e32 v35, v6, v32
	v_sub_f32_e32 v36, v7, v32
	v_exp_f32_e32 v6, v18
	v_exp_f32_e32 v7, v19
	v_sub_f32_e32 v20, v20, v32
	v_sub_f32_e32 v21, v21, v32
	v_sub_f32_e32 v37, v8, v32
	v_sub_f32_e32 v38, v9, v32
	v_sub_f32_e32 v41, v12, v32
	v_exp_f32_e32 v8, v33
	v_exp_f32_e32 v9, v34
	v_exp_f32_e32 v12, v35
	v_pk_add_f32 v[34:35], v[0:1], 0 op_sel_hi:[1,0]
	v_sub_f32_e32 v39, v10, v32
	v_sub_f32_e32 v40, v11, v32
	v_exp_f32_e32 v10, v20
	v_exp_f32_e32 v11, v21
	v_pk_add_f32 v[34:35], v[4:5], v[34:35]
	v_sub_f32_e32 v22, v22, v32
	v_sub_f32_e32 v23, v23, v32
	v_sub_f32_e32 v42, v13, v32
	v_exp_f32_e32 v13, v36
	v_pk_add_f32 v[34:35], v[2:3], v[34:35]
	v_sub_f32_e32 v43, v14, v32
	v_sub_f32_e32 v44, v15, v32
	v_exp_f32_e32 v14, v22
	v_exp_f32_e32 v15, v23
	v_pk_add_f32 v[34:35], v[6:7], v[34:35]
	v_sub_f32_e32 v24, v24, v32
	v_sub_f32_e32 v25, v25, v32
	v_exp_f32_e32 v16, v37
	v_exp_f32_e32 v17, v38
	v_pk_add_f32 v[34:35], v[8:9], v[34:35]
	v_exp_f32_e32 v18, v24
	v_exp_f32_e32 v19, v25
	v_pk_add_f32 v[34:35], v[10:11], v[34:35]
	v_sub_f32_e32 v26, v26, v32
	v_sub_f32_e32 v27, v27, v32
	v_exp_f32_e32 v20, v39
	v_exp_f32_e32 v21, v40
	v_pk_add_f32 v[34:35], v[12:13], v[34:35]
	v_exp_f32_e32 v22, v26
	v_exp_f32_e32 v23, v27
	v_pk_add_f32 v[34:35], v[14:15], v[34:35]
	v_sub_f32_e32 v28, v28, v32
	v_sub_f32_e32 v29, v29, v32
	v_exp_f32_e32 v24, v41
	v_exp_f32_e32 v25, v42
	v_pk_add_f32 v[34:35], v[16:17], v[34:35]
	v_exp_f32_e32 v26, v28
	v_exp_f32_e32 v27, v29
	v_pk_add_f32 v[34:35], v[18:19], v[34:35]
	v_sub_f32_e32 v30, v30, v32
	v_sub_f32_e32 v31, v31, v32
	v_exp_f32_e32 v28, v43
	v_exp_f32_e32 v29, v44
	v_pk_add_f32 v[34:35], v[20:21], v[34:35]
	v_exp_f32_e32 v30, v30
	v_exp_f32_e32 v31, v31
	v_pk_add_f32 v[34:35], v[22:23], v[34:35]
	v_cvt_pk_bf16_f32 v0, v0, v1
	v_pk_add_f32 v[34:35], v[24:25], v[34:35]
	v_cvt_pk_bf16_f32 v1, v2, v3
	v_pk_add_f32 v[34:35], v[26:27], v[34:35]
	v_cvt_pk_bf16_f32 v2, v8, v9
	v_pk_add_f32 v[34:35], v[28:29], v[34:35]
	v_cvt_pk_bf16_f32 v3, v12, v13
	v_pk_add_f32 v[34:35], v[30:31], v[34:35]
	v_cvt_pk_bf16_f32 v36, v4, v5
	v_pk_add_f32 v[34:35], v[34:35], v[34:35] op_sel_hi:[0,1]
	v_mov_b32_e32 v33, v35
	v_pk_add_f32 v[198:199], v[32:33], 0 op_sel_hi:[1,0]
	v_cvt_pk_bf16_f32 v32, v16, v17
	v_cvt_pk_bf16_f32 v33, v20, v21
	v_cvt_pk_bf16_f32 v34, v24, v25
	v_cvt_pk_bf16_f32 v35, v28, v29
	v_cvt_pk_bf16_f32 v37, v6, v7
	v_cvt_pk_bf16_f32 v38, v10, v11
	v_cvt_pk_bf16_f32 v39, v14, v15
	v_cvt_pk_bf16_f32 v40, v18, v19
	v_cvt_pk_bf16_f32 v41, v22, v23
	v_cvt_pk_bf16_f32 v42, v26, v27
	v_cvt_pk_bf16_f32 v43, v30, v31
	v_mfma_f32_32x32x16_bf16 v[16:31], v[66:69], v[0:3], 0
	v_add_f32_e64 v48, -v198, neg(0)
	v_add_f32_e64 v49, -v199, neg(0)
	s_waitcnt lgkmcnt(6)
	v_mfma_f32_32x32x16_bf16 v[0:15], v[102:105], v[0:3], 0
	v_mfma_f32_32x32x16_bf16 v[16:31], v[98:101], v[32:35], v[16:31]
	s_waitcnt lgkmcnt(4)
	v_mfma_f32_32x32x16_bf16 v[0:15], v[114:117], v[32:35], v[0:15]
	ds_read_b128 v[50:53], v184 offset:6720
	ds_read_b128 v[70:73], v184 offset:6752
	ds_read_b128 v[32:35], v184 offset:64
	ds_read_b128 v[74:77], v184 offset:96
	v_mfma_f32_32x32x16_bf16 v[16:31], v[94:97], v[36:39], v[16:31]
	s_waitcnt lgkmcnt(6)
	v_mfma_f32_32x32x16_bf16 v[0:15], v[110:113], v[36:39], v[0:15]
	v_mfma_f32_32x32x16_bf16 v[16:31], v[90:93], v[40:43], v[16:31]
	s_waitcnt lgkmcnt(4)
	v_mfma_f32_32x32x16_bf16 v[0:15], v[106:109], v[40:43], v[0:15]
	s_waitcnt lgkmcnt(1)
	v_mfma_f32_32x32x16_bf16 v[32:47], v[32:35], v[136:139], 0
	s_movk_i32 s7, 0x80
	v_mfma_f32_32x32x16_bf16 v[50:65], v[50:53], v[136:139], 0
	s_waitcnt lgkmcnt(0)
	v_mfma_f32_32x32x16_bf16 v[32:47], v[74:77], v[140:143], v[32:47]
	v_mfma_f32_32x32x16_bf16 v[50:65], v[70:73], v[140:143], v[50:65]
	s_nop 15
	s_nop 7
	s_waitcnt vmcnt(1)
	ds_write_b128 v241, v[82:85] offset:13312
	s_waitcnt vmcnt(0)
	ds_write_b128 v242, v[86:89] offset:38912
	v_max3_f32 v49, v32, v33, v50
	v_max3_f32 v70, v34, v35, v51
	s_waitcnt lgkmcnt(0)
	s_barrier
	v_max3_f32 v49, v49, v52, v53
	v_max3_f32 v70, v70, v38, v39
	s_nop 0
	v_max3_f32 v49, v49, v36, v37
	v_max3_f32 v70, v70, v56, v57
	s_nop 0
	v_max3_f32 v49, v49, v54, v55
	v_max3_f32 v70, v70, v42, v43
	s_nop 0
	v_max3_f32 v49, v49, v40, v41
	v_max3_f32 v70, v70, v60, v61
	s_nop 0
	v_max3_f32 v49, v49, v58, v59
	v_max3_f32 v70, v70, v46, v47
	s_nop 0
	v_max3_f32 v49, v49, v44, v45
	v_max3_f32 v70, v70, v64, v65
	s_nop 0
	v_max3_f32 v49, v49, v62, v63
	s_nop 0
	v_max_f32_e32 v49, v49, v70
	s_nop 0
	v_mov_b32_e32 v70, v49
	s_nop 1
	v_permlane32_swap_b32_e32 v49, v70
	v_max_f32_e32 v70, v70, v70
	v_max_f32_e32 v49, v49, v49
	v_max_f32_e32 v80, v49, v70
	v_sub_f32_e32 v32, v32, v80
	v_sub_f32_e32 v33, v33, v80
	v_sub_f32_e32 v34, v34, v80
	v_sub_f32_e32 v35, v35, v80
	v_sub_f32_e32 v36, v36, v80
	v_sub_f32_e32 v37, v37, v80
	v_sub_f32_e32 v38, v38, v80
	v_sub_f32_e32 v39, v39, v80
	v_sub_f32_e32 v49, v50, v80
	v_sub_f32_e32 v50, v51, v80
	v_sub_f32_e32 v51, v52, v80
	v_sub_f32_e32 v52, v53, v80
	v_sub_f32_e32 v53, v54, v80
	v_sub_f32_e32 v70, v55, v80
	v_sub_f32_e32 v125, v58, v80
	v_sub_f32_e32 v127, v59, v80
	v_sub_f32_e32 v150, v62, v80
	v_sub_f32_e32 v151, v63, v80
	v_exp_f32_e32 v54, v32
	v_exp_f32_e32 v55, v33
	v_exp_f32_e32 v58, v34
	v_exp_f32_e32 v59, v35
	v_exp_f32_e32 v62, v36
	v_exp_f32_e32 v63, v37
	v_exp_f32_e32 v120, v38
	v_exp_f32_e32 v121, v39
	v_sub_f32_e32 v71, v56, v80
	v_sub_f32_e32 v40, v40, v80
	v_sub_f32_e32 v41, v41, v80
	v_sub_f32_e32 v42, v42, v80
	v_sub_f32_e32 v43, v43, v80
	v_sub_f32_e32 v44, v44, v80
	v_cvt_pk_bf16_f32 v32, v54, v55
	v_cvt_pk_bf16_f32 v33, v58, v59
	v_cvt_pk_bf16_f32 v34, v62, v63
	v_cvt_pk_bf16_f32 v35, v120, v121
	v_sub_f32_e32 v147, v45, v80
	v_sub_f32_e32 v152, v46, v80
	v_sub_f32_e32 v153, v64, v80
	v_sub_f32_e32 v154, v47, v80
	v_sub_f32_e32 v155, v65, v80
	v_exp_f32_e32 v119, v70
	v_exp_f32_e32 v122, v71
	v_mfma_f32_32x32x16_bf16 v[64:79], v[66:69], v[32:35], 0
	v_exp_f32_e32 v124, v40
	v_exp_f32_e32 v126, v125
	v_exp_f32_e32 v125, v41
	v_exp_f32_e32 v144, v42
	v_exp_f32_e32 v145, v43
	v_exp_f32_e32 v146, v44
	v_exp_f32_e32 v147, v147
	v_mfma_f32_32x32x16_bf16 v[32:47], v[102:105], v[32:35], 0
	v_exp_f32_e32 v102, v152
	v_exp_f32_e32 v103, v154
	v_sub_f32_e32 v81, v57, v80
	v_sub_f32_e32 v148, v60, v80
	v_sub_f32_e32 v149, v61, v80
	v_exp_f32_e32 v57, v50
	v_exp_f32_e32 v60, v51
	v_exp_f32_e32 v61, v52
	v_exp_f32_e32 v118, v53
	v_cvt_pk_bf16_f32 v50, v124, v125
	v_cvt_pk_bf16_f32 v51, v144, v145
	v_cvt_pk_bf16_f32 v52, v146, v147
	v_cvt_pk_bf16_f32 v53, v102, v103
	v_exp_f32_e32 v56, v49
	v_exp_f32_e32 v123, v81
	v_mfma_f32_32x32x16_bf16 v[64:79], v[98:101], v[50:53], v[64:79]
	v_exp_f32_e32 v127, v127
	v_exp_f32_e32 v98, v148
	v_exp_f32_e32 v99, v149
	v_exp_f32_e32 v100, v150
	v_exp_f32_e32 v101, v151
	v_exp_f32_e32 v104, v153
	v_exp_f32_e32 v105, v155
	v_mfma_f32_32x32x16_bf16 v[32:47], v[114:117], v[50:53], v[32:47]
	v_add_f32_e64 v50, v54, 0
	v_add_f32_e64 v51, v55, 0
	v_cvt_pk_bf16_f32 v52, v118, v119
	v_add_f32_e64 v50, v56, v50
	v_add_f32_e64 v51, v57, v51
	v_cvt_pk_bf16_f32 v53, v122, v123
	v_pk_add_f32 v[54:55], v[58:59], v[50:51]
	v_cvt_pk_bf16_f32 v50, v56, v57
	v_pk_add_f32 v[54:55], v[60:61], v[54:55]
	v_cvt_pk_bf16_f32 v51, v60, v61
	v_pk_add_f32 v[54:55], v[62:63], v[54:55]
	v_mov_b32_e32 v49, v48
	v_mfma_f32_32x32x16_bf16 v[64:79], v[94:97], v[50:53], v[64:79]
	v_add_f32_e64 v54, v118, v54
	v_add_f32_e64 v55, v119, v55
	v_mov_b32_e32 v56, v48
	v_add_f32_e64 v54, v120, v54
	v_add_f32_e64 v55, v121, v55
	v_mov_b32_e32 v57, v48
	v_pk_add_f32 v[54:55], v[122:123], v[54:55]
	v_mov_b32_e32 v58, v48
	v_pk_add_f32 v[54:55], v[124:125], v[54:55]
	v_mfma_f32_32x32x16_bf16 v[32:47], v[110:113], v[50:53], v[32:47]
	v_add_f32_e64 v54, v126, v54
	v_add_f32_e64 v55, v127, v55
	v_cvt_pk_bf16_f32 v52, v100, v101
	v_add_f32_e64 v50, v144, v54
	v_add_f32_e64 v51, v145, v55
	v_cvt_pk_bf16_f32 v53, v104, v105
	v_pk_add_f32 v[50:51], v[98:99], v[50:51]
	v_mov_b32_e32 v59, v48
	v_pk_add_f32 v[54:55], v[146:147], v[50:51]
	v_cvt_pk_bf16_f32 v50, v126, v127
	v_cvt_pk_bf16_f32 v51, v98, v99
	v_pk_add_f32 v[54:55], v[100:101], v[54:55]
	v_mov_b32_e32 v60, v48
	v_mfma_f32_32x32x16_bf16 v[64:79], v[90:93], v[50:53], v[64:79]
	v_add_f32_e64 v54, v102, v54
	v_add_f32_e64 v55, v103, v55
	v_mov_b32_e32 v61, v48
	v_add_f32_e64 v54, v104, v54
	v_add_f32_e64 v55, v105, v55
	v_mov_b32_e32 v62, v48
	v_pk_add_f32 v[54:55], v[54:55], v[54:55] op_sel_hi:[0,1]
	v_mov_b32_e32 v81, v55
	v_pk_add_f32 v[200:201], v[80:81], 0 op_sel_hi:[1,0]
	v_mfma_f32_32x32x16_bf16 v[32:47], v[106:109], v[50:53], v[32:47]
	v_add_f32_e64 v80, -v200, neg(0)
	v_add_f32_e64 v81, -v201, neg(0)
	v_mov_b32_e32 v50, v48
	v_mov_b32_e32 v81, v80
	v_mov_b32_e32 v82, v80
	v_mov_b32_e32 v83, v80
	v_mov_b32_e32 v84, v80
	v_mov_b32_e32 v85, v80
	v_mov_b32_e32 v86, v80
	v_mov_b32_e32 v87, v80
	v_mov_b32_e32 v88, v80
	v_mov_b32_e32 v89, v80
	v_mov_b32_e32 v90, v80
	v_mov_b32_e32 v91, v80
	v_mov_b32_e32 v92, v80
	v_mov_b32_e32 v93, v80
	v_mov_b32_e32 v94, v80
	v_mov_b32_e32 v95, v80
	v_mov_b32_e32 v51, v48
	v_mov_b32_e32 v52, v48
	v_mov_b32_e32 v53, v48
	v_mov_b32_e32 v54, v48
	v_mov_b32_e32 v55, v48
	v_mov_b32_e32 v63, v48
	v_readlane_b32 s99, v255, 23
	s_nop 0
